# v15 + MLA norm/rope (MINI) phase: all row loads of both rows issued together behind one wait (were 3 serialized round trips), norm gains loaded once before the loop, no store-drain waits, global_ inst
# speedup vs baseline: 1.0099x; 1.0030x over previous
; __device__ __forceinline__ unsigned cvt_pk_bf16(float lo, float hi) { unsigned r; asm volatile("v_cvt_pk_bf16_f32 %0, %1, %2" : "=v"(r) : "v"(lo), "v"(hi)); return r; }
; __device__ __forceinline__ float bf_lo(unsigned w) { return __uint_as_float(w << 16); }
; __global__ void __launch_bounds__(512, 2) mega(Args a) {
;     ...
;                 const float* gq = INPTR(5) + (size_t)l * 384; const float* gkv = INPTR(7) + (size_t)l * 256;
;                 for (int m0 = gw * 2; m0 < Tc; m0 += NGW * 2) {
;                     u32x4 wq[2], wk[2]; float x1[2], x2[2]; f32x2 cs[2];
; #pragma unroll
;                     for (int rr = 0; rr < 2; ++rr) { const int m = m0 + rr; bf16_t* P = PROJ + (size_t)m * INP;
;                         wq[rr] = (u32x4){0u, 0u, 0u, 0u}; wk[rr] = (u32x4){0u, 0u, 0u, 0u}; x1[rr] = 0.f; x2[rr] = 0.f; cs[rr] = (f32x2){0.f, 0.f};
;                         if (lane < 48) wq[rr] = *(const u32x4*)(P + C_CQ + lane * 8);
;                         if (lane < 32) wk[rr] = *(const u32x4*)(P + C_CKV + lane * 8);
;                         if (lane < 16) { x1[rr] = bf1(P[C_KPE + lane]); x2[rr] = bf1(P[C_KPE + 16 + lane]); cs[rr] = rope[(m & (SEQ - 1)) * 16 + lane]; } }
;     ...
;                           if (lane < 48) { const f32x4 g0 = *(const f32x4*)(gq + lane * 8), g1 = *(const f32x4*)(gq + lane * 8 + 4); u32x4 o;
;                               o.x = cvt_pk_bf16(bf_lo(w.x) * rstd * g0.x, bf_hi(w.x) * rstd * g0.y); o.y = cvt_pk_bf16(bf_lo(w.y) * rstd * g0.z, bf_hi(w.y) * rstd * g0.w);
;                               o.z = cvt_pk_bf16(bf_lo(w.z) * rstd * g1.x, bf_hi(w.z) * rstd * g1.y); o.w = cvt_pk_bf16(bf_lo(w.w) * rstd * g1.z, bf_hi(w.w) * rstd * g1.w);
;                               *(u32x4*)(P + C_CQ + lane * 8) = o; } }
;                         { const u32x4 w = wk[rr];
;                           float ss = bf_lo(w.x) * bf_lo(w.x) + bf_hi(w.x) * bf_hi(w.x) + bf_lo(w.y) * bf_lo(w.y) + bf_hi(w.y) * bf_hi(w.y) + bf_lo(w.z) * bf_lo(w.z) + bf_hi(w.z) * bf_hi(w.z) + bf_lo(w.w) * bf_lo(w.w) + bf_hi(w.w) * bf_hi(w.w);
;                           const float rstd = __builtin_amdgcn_rsqf(wave_sum(ss) * (1.f / 256.f) + NORM_EPS);
;                           if (lane < 32) { const f32x4 g0 = *(const f32x4*)(gkv + lane * 8), g1 = *(const f32x4*)(gkv + lane * 8 + 4); u32x4 o;
.LBB0_1523:
	s_and_b64 vcc, exec, s[4:5]
	s_cbranch_vccz .LBB0_1551
	s_lshl_b32 s4, s83, 1
	s_mov_b32 s10, 5
	s_mov_b32 s8, 7
	s_cmp_ge_i32 s4, s16
	s_cbranch_scc1 .LBB0_1551
	s_ashr_i32 s11, s10, 31
	s_lshl_b64 s[6:7], s[10:11], 3
	s_add_u32 s6, s0, s6
	s_addc_u32 s7, s1, s7
	s_ashr_i32 s9, s8, 31
	s_lshl_b64 s[8:9], s[8:9], 3
	s_add_u32 s8, s0, s8
	s_addc_u32 s9, s1, s9
	s_load_dwordx2 s[8:9], s[8:9], 0x0
	v_readlane_b32 s12, v253, 50
	s_load_dwordx2 s[6:7], s[6:7], 0x0
	v_readlane_b32 s13, v253, 51
	s_lshl_b64 s[10:11], s[12:13], 10
	s_waitcnt lgkmcnt(0)
	s_add_u32 s8, s8, s10
	s_addc_u32 s9, s9, s11
	s_mul_i32 s10, s12, 0x600
	s_mul_hi_i32 s5, s12, 0x600
	s_add_u32 s6, s6, s10
	v_cmp_lt_i32_e32 vcc, v185, v184
	s_addc_u32 s7, s7, s5
	v_lshlrev_b32_e32 v4, 5, v203
	v_cndmask_b32_e32 v0, v183, v185, vcc
	v_cmp_lt_i32_e32 vcc, v186, v184
	v_lshlrev_b32_e32 v39, 2, v0
	v_lshl_add_u64 v[20:21], s[6:7], 0, v[4:5]
	v_cndmask_b32_e32 v0, v183, v186, vcc
	v_cmp_lt_i32_e32 vcc, v187, v184
	v_lshl_add_u64 v[22:23], s[8:9], 0, v[4:5]
	s_mul_i32 s6, s4, 0x3600
	v_readlane_b32 s8, v253, 60
	v_lshlrev_b32_e32 v40, 2, v0
	v_cndmask_b32_e32 v0, v183, v187, vcc
	v_cmp_lt_i32_e32 vcc, v188, v184
	s_mul_hi_i32 s5, s4, 0x3600
	v_readlane_b32 s9, v253, 61
	s_add_u32 s6, s6, s8
	v_lshlrev_b32_e32 v41, 2, v0
	v_cndmask_b32_e32 v0, v183, v188, vcc
	v_cmp_lt_i32_e32 vcc, v189, v184
	s_addc_u32 s5, s5, s9
	v_lshlrev_b32_e32 v42, 2, v0
	v_cndmask_b32_e32 v0, v183, v189, vcc
	v_cmp_lt_i32_e32 vcc, v190, v184
	s_add_u32 s8, s74, s6
	v_lshlrev_b32_e32 v43, 2, v0
	v_cndmask_b32_e32 v0, v183, v190, vcc
	s_addc_u32 s9, s75, s5
	s_lshl_b32 s5, s92, 5
	v_readlane_b32 s6, v253, 16
	v_cmp_gt_u32_e64 s[40:41], 48, v203
	v_cmp_gt_u32_e64 s[42:43], 32, v203
	v_cmp_gt_u32_e64 s[44:45], 16, v203
	v_lshlrev_b32_e32 v44, 2, v0
	v_lshlrev_b32_e32 v24, 4, v203
	v_mov_b32_e32 v25, v5
	v_lshlrev_b32_e32 v26, 1, v203
	v_mov_b32_e32 v27, v5
	s_add_i32 s5, s6, s5
	v_mov_b32_e32 v64, 0
	v_mov_b32_e32 v65, 0
	v_mov_b32_e32 v66, 0
	v_mov_b32_e32 v67, 0
	v_mov_b32_e32 v68, 0
	v_mov_b32_e32 v69, 0
	v_mov_b32_e32 v70, 0
	v_mov_b32_e32 v71, 0
	v_mov_b32_e32 v72, 0
	v_mov_b32_e32 v73, 0
	v_mov_b32_e32 v74, 0
	v_mov_b32_e32 v75, 0
	v_mov_b32_e32 v76, 0
	v_mov_b32_e32 v77, 0
	v_mov_b32_e32 v78, 0
	v_mov_b32_e32 v79, 0
	s_and_saveexec_b64 s[10:11], s[40:41]
	global_load_dwordx4 v[64:67], v[20:21], off
	global_load_dwordx4 v[68:71], v[20:21], off offset:16
	s_mov_b64 exec, s[10:11]
	s_and_saveexec_b64 s[10:11], s[42:43]
	global_load_dwordx4 v[72:75], v[22:23], off
	global_load_dwordx4 v[76:79], v[22:23], off offset:16
	s_mov_b64 exec, s[10:11]
	s_waitcnt vmcnt(0)
	s_branch .LBB0_1527

; __device__ __forceinline__ float bf_lo(unsigned w) { return __uint_as_float(w << 16); }
; __global__ void __launch_bounds__(512, 2) mega(Args a) {
;     ...
;                     u32x4 wq[2], wk[2]; float x1[2], x2[2]; f32x2 cs[2];
; #pragma unroll
;                     for (int rr = 0; rr < 2; ++rr) { const int m = m0 + rr; bf16_t* P = PROJ + (size_t)m * INP;
;                         wq[rr] = (u32x4){0u, 0u, 0u, 0u}; wk[rr] = (u32x4){0u, 0u, 0u, 0u}; x1[rr] = 0.f; x2[rr] = 0.f; cs[rr] = (f32x2){0.f, 0.f};
;                         if (lane < 48) wq[rr] = *(const u32x4*)(P + C_CQ + lane * 8);
;                         if (lane < 32) wk[rr] = *(const u32x4*)(P + C_CKV + lane * 8);
;                         if (lane < 16) { x1[rr] = bf1(P[C_KPE + lane]); x2[rr] = bf1(P[C_KPE + 16 + lane]); cs[rr] = rope[(m & (SEQ - 1)) * 16 + lane]; } }
; #pragma unroll
;                     for (int rr = 0; rr < 2; ++rr) { const int m = m0 + rr; bf16_t* P = PROJ + (size_t)m * INP;
;                         { const u32x4 w = wq[rr];
;                           float ss = bf_lo(w.x) * bf_lo(w.x) + bf_hi(w.x) * bf_hi(w.x) + bf_lo(w.y) * bf_lo(w.y) + bf_hi(w.y) * bf_hi(w.y) + bf_lo(w.z) * bf_lo(w.z) + bf_hi(w.z) * bf_hi(w.z) + bf_lo(w.w) * bf_lo(w.w) + bf_hi(w.w) * bf_hi(w.w);
;                           const float rstd = __builtin_amdgcn_rsqf(wave_sum(ss) * (1.f / 384.f) + NORM_EPS);
;                           if (lane < 48) { const f32x4 g0 = *(const f32x4*)(gq + lane * 8), g1 = *(const f32x4*)(gq + lane * 8 + 4); u32x4 o;
;                               o.x = cvt_pk_bf16(bf_lo(w.x) * rstd * g0.x, bf_hi(w.x) * rstd * g0.y); o.y = cvt_pk_bf16(bf_lo(w.y) * rstd * g0.z, bf_hi(w.y) * rstd * g0.w);
;                               o.z = cvt_pk_bf16(bf_lo(w.z) * rstd * g1.x, bf_hi(w.z) * rstd * g1.y); o.w = cvt_pk_bf16(bf_lo(w.w) * rstd * g1.z, bf_hi(w.w) * rstd * g1.w);
;                               *(u32x4*)(P + C_CQ + lane * 8) = o; } }
;                         { const u32x4 w = wk[rr];
;                           float ss = bf_lo(w.x) * bf_lo(w.x) + bf_hi(w.x) * bf_hi(w.x) + bf_lo(w.y) * bf_lo(w.y) + bf_hi(w.y) * bf_hi(w.y) + bf_lo(w.z) * bf_lo(w.z) + bf_hi(w.z) * bf_hi(w.z) + bf_lo(w.w) * bf_lo(w.w) + bf_hi(w.w) * bf_hi(w.w);
;                           const float rstd = __builtin_amdgcn_rsqf(wave_sum(ss) * (1.f / 256.f) + NORM_EPS);
.LBB0_1527:
	v_lshl_add_u64 v[28:29], s[8:9], 0, v[24:25]
	v_lshl_add_u64 v[30:31], s[8:9], 0, v[26:27]
	v_mov_b32_e32 v8, 0
	v_mov_b32_e32 v9, 0
	v_mov_b32_e32 v10, 0
	v_mov_b32_e32 v11, 0
	v_mov_b32_e32 v12, 0
	v_mov_b32_e32 v13, 0
	v_mov_b32_e32 v14, 0
	v_mov_b32_e32 v15, 0
	v_mov_b32_e32 v16, 0
	v_mov_b32_e32 v17, 0
	v_mov_b32_e32 v18, 0
	v_mov_b32_e32 v19, 0
	v_mov_b32_e32 v0, 0
	v_mov_b32_e32 v1, 0
	v_mov_b32_e32 v2, 0
	v_mov_b32_e32 v3, 0
	v_mov_b32_e32 v36, 0
	v_mov_b32_e32 v37, 0
	v_mov_b32_e32 v34, 0
	v_mov_b32_e32 v35, 0
	v_mov_b32_e32 v58, 0
	v_mov_b32_e32 v59, 0
	v_mov_b32_e32 v60, 0
	v_mov_b32_e32 v61, 0
	v_add_co_u32_e32 v50, vcc, 0x5003000, v28
	s_nop 1
	v_addc_co_u32_e32 v51, vcc, 0, v29, vcc
	v_add_co_u32_e32 v52, vcc, 0x5006000, v28
	s_nop 1
	v_addc_co_u32_e32 v53, vcc, 0, v29, vcc
	v_add_co_u32_e32 v54, vcc, 0x5003000, v30
	s_nop 1
	v_addc_co_u32_e32 v55, vcc, 0, v31, vcc
	v_add_co_u32_e32 v56, vcc, 0x5006000, v30
	s_nop 1
	v_addc_co_u32_e32 v57, vcc, 0, v31, vcc
	s_and_b32 s6, s5, 0x7fe0
	v_or_b32_e32 v4, s6, v203
	v_lshlrev_b32_e32 v4, 3, v4
	s_add_i32 s6, s5, 16
	s_and_b32 s6, s6, 0x7ff0
	v_or_b32_e32 v6, s6, v203
	v_lshlrev_b32_e32 v6, 3, v6
	v_mov_b32_e32 v7, 0
	v_readlane_b32 s6, v253, 42
	v_readlane_b32 s7, v253, 43
	s_nop 1
	v_lshl_add_u64 v[62:63], s[6:7], 0, v[4:5]
	v_lshl_add_u64 v[46:47], s[6:7], 0, v[6:7]
	s_and_saveexec_b64 s[10:11], s[40:41]
	global_load_dwordx4 v[8:11], v[50:51], off
	global_load_dwordx4 v[12:15], v[52:53], off offset:1536
	s_mov_b64 exec, s[10:11]
	s_and_saveexec_b64 s[10:11], s[42:43]
	global_load_dwordx4 v[16:19], v[50:51], off offset:768
	global_load_dwordx4 v[0:3], v[52:53], off offset:2304
	s_mov_b64 exec, s[10:11]
	s_and_saveexec_b64 s[10:11], s[44:45]
	global_load_ushort v58, v[54:55], off offset:1280
	global_load_ushort v59, v[54:55], off offset:1312
	global_load_ushort v60, v[56:57], off offset:2816
	global_load_ushort v61, v[56:57], off offset:2848
	global_load_dwordx2 v[36:37], v[62:63], off
	global_load_dwordx2 v[34:35], v[46:47], off
	s_mov_b64 exec, s[10:11]
	s_waitcnt vmcnt(0)
	v_lshlrev_b32_e32 v38, 16, v58
	v_lshlrev_b32_e32 v32, 16, v59
	v_lshlrev_b32_e32 v7, 16, v60
	v_lshlrev_b32_e32 v33, 16, v61
.LBB0_1539:
	s_or_b64 exec, exec, s[10:11]
	v_and_b32_e32 v6, 0xffff0000, v8
	v_lshlrev_b32_e32 v4, 16, v8
	v_mul_f32_e32 v47, v6, v6
	v_fmac_f32_e32 v47, v4, v4
	v_lshlrev_b32_e32 v8, 16, v9
	v_fmac_f32_e32 v47, v8, v8
	v_and_b32_e32 v9, 0xffff0000, v9
	v_fmac_f32_e32 v47, v9, v9
	v_lshlrev_b32_e32 v45, 16, v10
	v_fmac_f32_e32 v47, v45, v45
	v_and_b32_e32 v10, 0xffff0000, v10
	v_fmac_f32_e32 v47, v10, v10
	v_lshlrev_b32_e32 v46, 16, v11
	v_fmac_f32_e32 v47, v46, v46
	v_and_b32_e32 v11, 0xffff0000, v11
	v_fmac_f32_e32 v47, v11, v11
	ds_bpermute_b32 v48, v39, v47
	s_waitcnt lgkmcnt(0)
	v_add_f32_e32 v47, v47, v48
	ds_bpermute_b32 v48, v40, v47
	s_waitcnt lgkmcnt(0)
	v_add_f32_e32 v47, v47, v48
	ds_bpermute_b32 v48, v41, v47
	s_waitcnt lgkmcnt(0)
	v_add_f32_e32 v47, v47, v48
	ds_bpermute_b32 v48, v42, v47
	s_waitcnt lgkmcnt(0)
	v_add_f32_e32 v47, v47, v48
	ds_bpermute_b32 v48, v43, v47
	s_waitcnt lgkmcnt(0)
	v_add_f32_e32 v47, v47, v48
	ds_bpermute_b32 v48, v44, v47
	s_and_saveexec_b64 s[10:11], s[40:41]
	s_cbranch_execz .LBB0_1541
	s_waitcnt lgkmcnt(0)
	v_add_f32_e32 v47, v47, v48
	v_fmamk_f32 v47, v47, 0x3b2aaaab, v192
	v_rsq_f32_e32 v47, v47
	v_add_co_u32_e32 v48, vcc, 0x5003000, v28
	v_mul_f32_e32 v9, v47, v9
	v_mul_f32_e32 v10, v47, v10
	v_mul_f32_e32 v11, v47, v11
	v_mul_f32_e32 v4, v47, v4
	v_mul_f32_e32 v6, v47, v6
	v_mul_f32_e32 v8, v47, v8
	v_mul_f32_e32 v45, v47, v45
	v_mul_f32_e32 v46, v47, v46
	v_addc_co_u32_e32 v49, vcc, 0, v29, vcc
	v_mul_f32_e32 v9, v9, v67
	v_mul_f32_e32 v10, v10, v69
	v_mul_f32_e32 v11, v11, v71
	v_mul_f32_e32 v4, v4, v64
	v_mul_f32_e32 v6, v6, v65
	v_mul_f32_e32 v47, v8, v66
	v_mul_f32_e32 v45, v45, v68
	v_mul_f32_e32 v46, v46, v70
	v_cvt_pk_bf16_f32 v8, v4, v6
	v_cvt_pk_bf16_f32 v9, v47, v9
	v_cvt_pk_bf16_f32 v10, v45, v10
	v_cvt_pk_bf16_f32 v11, v46, v11
	global_store_dwordx4 v[48:49], v[8:11], off
.LBB0_1541:
	s_or_b64 exec, exec, s[10:11]
	v_and_b32_e32 v6, 0xffff0000, v16
	v_lshlrev_b32_e32 v4, 16, v16
	v_mul_f32_e32 v45, v6, v6
	v_fmac_f32_e32 v45, v4, v4
	v_lshlrev_b32_e32 v8, 16, v17
	v_fmac_f32_e32 v45, v8, v8
	v_and_b32_e32 v9, 0xffff0000, v17
	v_fmac_f32_e32 v45, v9, v9
	v_lshlrev_b32_e32 v10, 16, v18
	v_fmac_f32_e32 v45, v10, v10
	v_and_b32_e32 v11, 0xffff0000, v18
	v_fmac_f32_e32 v45, v11, v11
	v_lshlrev_b32_e32 v16, 16, v19
	v_fmac_f32_e32 v45, v16, v16
	v_and_b32_e32 v17, 0xffff0000, v19
	v_fmac_f32_e32 v45, v17, v17
	ds_bpermute_b32 v18, v39, v45
	s_waitcnt lgkmcnt(0)
	v_add_f32_e32 v18, v45, v18
	ds_bpermute_b32 v19, v40, v18
	s_waitcnt lgkmcnt(0)
	v_add_f32_e32 v18, v18, v19
	ds_bpermute_b32 v19, v41, v18
	s_waitcnt lgkmcnt(0)
	v_add_f32_e32 v18, v18, v19
	ds_bpermute_b32 v19, v42, v18
	s_waitcnt lgkmcnt(0)
	v_add_f32_e32 v18, v18, v19
	ds_bpermute_b32 v19, v43, v18
	s_waitcnt lgkmcnt(0)
	v_add_f32_e32 v18, v18, v19
	ds_bpermute_b32 v19, v44, v18
	s_and_saveexec_b64 s[10:11], s[42:43]
	s_cbranch_execz .LBB0_1543
	s_waitcnt lgkmcnt(0)
	v_add_f32_e32 v18, v18, v19
	v_fmamk_f32 v18, v18, 0x3b800000, v192
	v_rsq_f32_e32 v19, v18
	v_add_co_u32_e32 v18, vcc, 0x5003000, v28
	v_mul_f32_e32 v8, v19, v8
	v_mul_f32_e32 v9, v19, v9
	v_mul_f32_e32 v4, v19, v4
	v_mul_f32_e32 v6, v19, v6
	v_mul_f32_e32 v10, v19, v10
	v_mul_f32_e32 v11, v19, v11
	v_mul_f32_e32 v16, v19, v16
	v_mul_f32_e32 v17, v19, v17
	v_mul_f32_e32 v19, v8, v74
	v_mul_f32_e32 v9, v9, v75
	v_mul_f32_e32 v4, v4, v72
	v_mul_f32_e32 v6, v6, v73
	v_mul_f32_e32 v10, v10, v76
	v_mul_f32_e32 v11, v11, v77
	v_cvt_pk_bf16_f32 v8, v4, v6
	v_cvt_pk_bf16_f32 v9, v19, v9
	v_addc_co_u32_e32 v19, vcc, 0, v29, vcc
	v_mul_f32_e32 v16, v16, v78
	v_mul_f32_e32 v17, v17, v79
	v_cvt_pk_bf16_f32 v10, v10, v11
	v_cvt_pk_bf16_f32 v11, v16, v17
	global_store_dwordx4 v[18:19], v[8:11], off offset:768
; __global__ void __launch_bounds__(512, 2) mega(Args a) {
;     ...
;                     for (int rr = 0; rr < 2; ++rr) { const int m = m0 + rr; bf16_t* P = PROJ + (size_t)m * INP;
;                         { const u32x4 w = wq[rr];
;                           float ss = bf_lo(w.x) * bf_lo(w.x) + bf_hi(w.x) * bf_hi(w.x) + bf_lo(w.y) * bf_lo(w.y) + bf_hi(w.y) * bf_hi(w.y) + bf_lo(w.z) * bf_lo(w.z) + bf_hi(w.z) * bf_hi(w.z) + bf_lo(w.w) * bf_lo(w.w) + bf_hi(w.w) * bf_hi(w.w);
;                           const float rstd = __builtin_amdgcn_rsqf(wave_sum(ss) * (1.f / 384.f) + NORM_EPS);
;                           if (lane < 48) { const f32x4 g0 = *(const f32x4*)(gq + lane * 8), g1 = *(const f32x4*)(gq + lane * 8 + 4); u32x4 o;
;                               o.x = cvt_pk_bf16(bf_lo(w.x) * rstd * g0.x, bf_hi(w.x) * rstd * g0.y); o.y = cvt_pk_bf16(bf_lo(w.y) * rstd * g0.z, bf_hi(w.y) * rstd * g0.w);
;                               o.z = cvt_pk_bf16(bf_lo(w.z) * rstd * g1.x, bf_hi(w.z) * rstd * g1.y); o.w = cvt_pk_bf16(bf_lo(w.w) * rstd * g1.z, bf_hi(w.w) * rstd * g1.w);
;                               *(u32x4*)(P + C_CQ + lane * 8) = o; } }
;                         { const u32x4 w = wk[rr];
;                           float ss = bf_lo(w.x) * bf_lo(w.x) + bf_hi(w.x) * bf_hi(w.x) + bf_lo(w.y) * bf_lo(w.y) + bf_hi(w.y) * bf_hi(w.y) + bf_lo(w.z) * bf_lo(w.z) + bf_hi(w.z) * bf_hi(w.z) + bf_lo(w.w) * bf_lo(w.w) + bf_hi(w.w) * bf_hi(w.w);
;                           const float rstd = __builtin_amdgcn_rsqf(wave_sum(ss) * (1.f / 256.f) + NORM_EPS);
;                           if (lane < 32) { const f32x4 g0 = *(const f32x4*)(gkv + lane * 8), g1 = *(const f32x4*)(gkv + lane * 8 + 4); u32x4 o;
;                               o.x = cvt_pk_bf16(bf_lo(w.x) * rstd * g0.x, bf_hi(w.x) * rstd * g0.y); o.y = cvt_pk_bf16(bf_lo(w.y) * rstd * g0.z, bf_hi(w.y) * rstd * g0.w);
;                               o.z = cvt_pk_bf16(bf_lo(w.z) * rstd * g1.x, bf_hi(w.z) * rstd * g1.y); o.w = cvt_pk_bf16(bf_lo(w.w) * rstd * g1.z, bf_hi(w.w) * rstd * g1.w);
;                               *(u32x4*)(P + C_CKV + lane * 8) = o; } }
;                         if (lane < 16) { const unsigned w = cvt_pk_bf16(x1[rr] * cs[rr].x - x2[rr] * cs[rr].y, x1[rr] * cs[rr].y + x2[rr] * cs[rr].x);
;                             P[C_KPE + lane] = (bf16_t)(w & 0xffff); P[C_KPE + 16 + lane] = (bf16_t)(w >> 16); }
.LBB0_1543:
	s_or_b64 exec, exec, s[10:11]
	s_and_saveexec_b64 s[10:11], s[44:45]
	s_cbranch_execz .LBB0_1545
	v_mul_f32_e32 v4, v32, v37
	v_fma_f32 v4, v38, v36, -v4
	v_mul_f32_e32 v6, v38, v37
	v_add_co_u32_e32 v8, vcc, 0x5003000, v30
	v_fmac_f32_e32 v6, v32, v36
	v_cvt_pk_bf16_f32 v4, v4, v6
	s_nop 0
	v_addc_co_u32_e32 v9, vcc, 0, v31, vcc
	global_store_short v[8:9], v4, off offset:1280
	global_store_short_d16_hi v[8:9], v4, off offset:1312
.LBB0_1545:
	s_or_b64 exec, exec, s[10:11]
	v_and_b32_e32 v6, 0xffff0000, v12
	v_lshlrev_b32_e32 v4, 16, v12
	v_mul_f32_e32 v16, v6, v6
	v_fmac_f32_e32 v16, v4, v4
	v_lshlrev_b32_e32 v8, 16, v13
	v_fmac_f32_e32 v16, v8, v8
	v_and_b32_e32 v9, 0xffff0000, v13
	v_fmac_f32_e32 v16, v9, v9
	v_lshlrev_b32_e32 v10, 16, v14
	v_fmac_f32_e32 v16, v10, v10
	v_and_b32_e32 v11, 0xffff0000, v14
	v_fmac_f32_e32 v16, v11, v11
	v_lshlrev_b32_e32 v12, 16, v15
	v_fmac_f32_e32 v16, v12, v12
	v_and_b32_e32 v13, 0xffff0000, v15
	v_fmac_f32_e32 v16, v13, v13
	ds_bpermute_b32 v14, v39, v16
	s_waitcnt lgkmcnt(0)
	v_add_f32_e32 v14, v16, v14
	ds_bpermute_b32 v15, v40, v14
	s_waitcnt lgkmcnt(0)
	v_add_f32_e32 v14, v14, v15
	ds_bpermute_b32 v15, v41, v14
	s_waitcnt lgkmcnt(0)
	v_add_f32_e32 v14, v14, v15
	ds_bpermute_b32 v15, v42, v14
	s_waitcnt lgkmcnt(0)
	v_add_f32_e32 v14, v14, v15
	ds_bpermute_b32 v15, v43, v14
	s_waitcnt lgkmcnt(0)
	v_add_f32_e32 v14, v14, v15
	ds_bpermute_b32 v15, v44, v14
	s_and_saveexec_b64 s[10:11], s[40:41]
	s_cbranch_execz .LBB0_1547
	s_waitcnt lgkmcnt(0)
	v_add_f32_e32 v14, v14, v15
	v_fmamk_f32 v14, v14, 0x3b2aaaab, v192
	v_rsq_f32_e32 v15, v14
	v_add_co_u32_e32 v14, vcc, 0x5006000, v28
	v_mul_f32_e32 v8, v15, v8
	v_mul_f32_e32 v9, v15, v9
	v_mul_f32_e32 v4, v15, v4
	v_mul_f32_e32 v6, v15, v6
	v_mul_f32_e32 v10, v15, v10
	v_mul_f32_e32 v11, v15, v11
	v_mul_f32_e32 v12, v15, v12
	v_mul_f32_e32 v13, v15, v13
	v_mul_f32_e32 v15, v8, v66
	v_mul_f32_e32 v9, v9, v67
	v_mul_f32_e32 v4, v4, v64
	v_mul_f32_e32 v6, v6, v65
	v_mul_f32_e32 v10, v10, v68
	v_mul_f32_e32 v11, v11, v69
	v_cvt_pk_bf16_f32 v8, v4, v6
	v_cvt_pk_bf16_f32 v9, v15, v9
	v_addc_co_u32_e32 v15, vcc, 0, v29, vcc
	v_mul_f32_e32 v12, v12, v70
	v_mul_f32_e32 v13, v13, v71
	v_cvt_pk_bf16_f32 v10, v10, v11
	v_cvt_pk_bf16_f32 v11, v12, v13
	global_store_dwordx4 v[14:15], v[8:11], off offset:1536
.LBB0_1547:
	s_or_b64 exec, exec, s[10:11]
	v_lshlrev_b32_e32 v4, 16, v0
	v_and_b32_e32 v0, 0xffff0000, v0
	v_mul_f32_e32 v10, v0, v0
	v_fmac_f32_e32 v10, v4, v4
	v_lshlrev_b32_e32 v6, 16, v1
	v_fmac_f32_e32 v10, v6, v6
	v_and_b32_e32 v1, 0xffff0000, v1
	v_fmac_f32_e32 v10, v1, v1
	v_lshlrev_b32_e32 v8, 16, v2
	v_fmac_f32_e32 v10, v8, v8
	v_and_b32_e32 v2, 0xffff0000, v2
	v_fmac_f32_e32 v10, v2, v2
	v_lshlrev_b32_e32 v9, 16, v3
	v_fmac_f32_e32 v10, v9, v9
	v_and_b32_e32 v3, 0xffff0000, v3
	v_fmac_f32_e32 v10, v3, v3
	ds_bpermute_b32 v11, v39, v10
	s_waitcnt lgkmcnt(0)
	v_add_f32_e32 v10, v10, v11
	ds_bpermute_b32 v11, v40, v10
	s_waitcnt lgkmcnt(0)
	v_add_f32_e32 v10, v10, v11
	ds_bpermute_b32 v11, v41, v10
	s_waitcnt lgkmcnt(0)
	v_add_f32_e32 v10, v10, v11
	ds_bpermute_b32 v11, v42, v10
	s_waitcnt lgkmcnt(0)
	v_add_f32_e32 v10, v10, v11
	ds_bpermute_b32 v11, v43, v10
	s_waitcnt lgkmcnt(0)
	v_add_f32_e32 v10, v10, v11
	ds_bpermute_b32 v11, v44, v10
	s_and_saveexec_b64 s[10:11], s[42:43]
	s_cbranch_execz .LBB0_1549
	s_waitcnt lgkmcnt(0)
	v_add_f32_e32 v10, v10, v11
	v_fmamk_f32 v10, v10, 0x3b800000, v192
	v_rsq_f32_e32 v11, v10
	v_add_co_u32_e32 v10, vcc, 0x5006000, v28
	v_mul_f32_e32 v0, v11, v0
	v_mul_f32_e32 v1, v11, v1
	v_mul_f32_e32 v2, v11, v2
	v_mul_f32_e32 v3, v11, v3
	v_mul_f32_e32 v4, v11, v4
	v_mul_f32_e32 v6, v11, v6
	v_mul_f32_e32 v8, v11, v8
	v_mul_f32_e32 v9, v11, v9
	v_addc_co_u32_e32 v11, vcc, 0, v29, vcc
	v_mul_f32_e32 v0, v0, v73
	v_mul_f32_e32 v1, v1, v75
	v_mul_f32_e32 v2, v2, v77
	v_mul_f32_e32 v3, v3, v79
	v_mul_f32_e32 v4, v4, v72
	v_mul_f32_e32 v6, v6, v74
	v_mul_f32_e32 v8, v8, v76
	v_mul_f32_e32 v9, v9, v78
	v_cvt_pk_bf16_f32 v0, v4, v0
	v_cvt_pk_bf16_f32 v1, v6, v1
	v_cvt_pk_bf16_f32 v2, v8, v2
	v_cvt_pk_bf16_f32 v3, v9, v3
	global_store_dwordx4 v[10:11], v[0:3], off offset:2304
.LBB0_1549:
	s_or_b64 exec, exec, s[10:11]
	s_and_saveexec_b64 s[10:11], s[44:45]
	s_cbranch_execz .LBB0_1526
	v_mul_f32_e32 v0, v33, v35
	v_fma_f32 v0, v7, v34, -v0
	v_mul_f32_e32 v1, v7, v35
	v_fmac_f32_e32 v1, v33, v34
	v_cvt_pk_bf16_f32 v2, v0, v1
	v_add_co_u32_e32 v0, vcc, 0x5006000, v30
	s_nop 1
	v_addc_co_u32_e32 v1, vcc, 0, v31, vcc
	global_store_short v[0:1], v2, off offset:2816
	global_store_short_d16_hi v[0:1], v2, off offset:2848
	s_branch .LBB0_1526
